# barrier B completion polled during LRU pass A (one load per chunk), invalidate issued as soon as complete; the blocking wait after pass A removed
# speedup vs baseline: 1.0009x; 1.0009x over previous
.LBB0_355:
	s_or_b64 exec, exec, s[46:47]
	s_andn2_b64 vcc, exec, s[48:49]
	s_cbranch_vccnz .LBB0_359
	s_xor_b32 s7, s4, 1
	s_mulk_i32 s7, 0x4a40
	s_add_i32 s7, s7, 0
	s_waitcnt lgkmcnt(3)
	v_add3_u32 v0, s7, v89, v90
	s_waitcnt vmcnt(0)
	s_cmp_eq_u32 s99, 0
	s_cbranch_scc1 .Lls_skip
	s_cmp_eq_u32 s99, 1
	s_cbranch_scc0 .Lls_st2
	s_and_saveexec_b64 s[100:101], s[56:57]
	s_cbranch_execz .Lls_1x
	v_mov_b32_e32 v246, 0x20ff0
	ds_read_b32 v246, v246
	s_waitcnt vmcnt(0) lgkmcnt(0)
	v_add_u32_e32 v247, 1, v247
	v_cmp_eq_u32_e32 vcc, v247, v246
	s_cbranch_vccz .Lls_1n
	buffer_wbl2 sc1
	s_waitcnt vmcnt(0)
	v_readlane_b32 s98, v242, 47
	s_nop 3
	s_cmp_eq_u32 s98, 0
	s_cselect_b32 s98, 0, 8
	s_add_u32 s98, s98, 0x16370d04
	s_add_u32 s98, s68, s98
	s_addc_u32 s99, s69, 0
	v_mov_b32_e32 v246, 0
	v_mov_b32_e32 v247, 1
	global_atomic_add v246, v247, s[98:99]
	s_waitcnt vmcnt(0)
.Lls_1n:
	v_readlane_b32 s98, v242, 47
	s_nop 3
	s_cmp_eq_u32 s98, 0
	s_cselect_b32 s98, 0, 8
	s_add_u32 s98, s98, 0x16370d04
	s_add_u32 s98, s68, s98
	s_addc_u32 s99, s69, 0
	v_mov_b32_e32 v246, 0
	global_load_dword v246, v246, s[98:99] sc1
.Lls_1x:
	s_or_b64 exec, exec, s[100:101]
	s_mov_b32 s99, 2
	s_branch .Lls_skip
.Lls_st2:
	s_and_saveexec_b64 s[100:101], s[56:57]
	s_mov_b32 s99, 2
	s_cbranch_execz .Lls_2x
	v_mov_b32_e32 v247, 0x20ff4
	ds_read_b32 v247, v247
	s_waitcnt lgkmcnt(0)
	v_cmp_lt_u32_e32 vcc, v246, v247
	s_cbranch_vccz .Lls_2d
	v_readlane_b32 s98, v242, 47
	s_nop 3
	s_cmp_eq_u32 s98, 0
	s_cselect_b32 s98, 0, 8
	s_add_u32 s98, s98, 0x16370d04
	s_add_u32 s98, s68, s98
	s_addc_u32 s99, s69, 0
	v_mov_b32_e32 v246, 0
	global_load_dword v246, v246, s[98:99] sc1
	s_mov_b32 s99, 2
	s_branch .Lls_2x
.Lls_2d:
	buffer_inv sc1
	s_mov_b32 s99, 0
.Lls_2x:
	s_or_b64 exec, exec, s[100:101]
.Lls_skip:
	ds_write_b128 v0, v[36:39] offset:35104
	ds_write_b128 v0, v[32:35] offset:35120
	s_and_saveexec_b64 s[46:47], s[40:41]
	s_cbranch_execz .LBB0_358
	v_add3_u32 v0, s7, v91, v90
	ds_write_b128 v0, v[44:47] offset:34816
	ds_write_b128 v0, v[40:43] offset:34832

.LBB0_361:
	s_waitcnt vmcnt(0)
	s_and_saveexec_b64 s[100:101], s[56:57]
	s_cbranch_execz .Lf_x
	s_cmp_eq_u32 s99, 0
	s_cbranch_scc1 .Lf_x
	s_cmp_eq_u32 s99, 1
	s_cbranch_scc0 .Lf_poll
	v_mov_b32_e32 v246, 0x20ff0
	ds_read_b32 v246, v246
	s_waitcnt vmcnt(0) lgkmcnt(0)
	v_add_u32_e32 v247, 1, v247
	v_cmp_eq_u32_e32 vcc, v247, v246
	s_cbranch_vccz .Lf_poll
	buffer_wbl2 sc1
	s_waitcnt vmcnt(0)
	v_readlane_b32 s98, v242, 47
	s_nop 3
	s_cmp_eq_u32 s98, 0
	s_cselect_b32 s98, 0, 8
	s_add_u32 s98, s98, 0x16370d04
	s_add_u32 s98, s68, s98
	s_addc_u32 s99, s69, 0
	v_mov_b32_e32 v246, 0
	v_mov_b32_e32 v247, 1
	global_atomic_add v246, v247, s[98:99]
	s_waitcnt vmcnt(0)
.Lf_poll:
	v_readlane_b32 s98, v242, 47
	s_nop 3
	s_cmp_eq_u32 s98, 0
	s_cselect_b32 s98, 0, 8
	s_add_u32 s98, s98, 0x16370d04
	s_add_u32 s98, s68, s98
	s_addc_u32 s99, s69, 0
	v_mov_b32_e32 v247, 0x20ff4
	ds_read_b32 v247, v247
	v_mov_b32_e32 v245, 0
	s_waitcnt lgkmcnt(0)

.Lf_x:
	s_or_b64 exec, exec, s[100:101]
	s_mov_b32 s99, 0
	v_mov_b32_e32 v245, 0xc0135761
	s_barrier
	s_and_saveexec_b64 s[100:101], s[56:57]
	s_and_b32 s98, s2, 15
	s_lshl_b32 s99, s96, 4
	s_add_i32 s98, s98, s99
	s_lshl_b32 s98, s98, 2
	s_add_u32 s98, s98, 0x16370d80
	s_add_u32 s98, s68, s98
	s_addc_u32 s99, s69, 0
	v_mov_b32_e32 v246, 0
	v_mov_b32_e32 v247, 1
	global_atomic_add v246, v247, s[98:99]
	s_or_b64 exec, exec, s[100:101]
	v_writelane_b32 v242, s10, 48
	s_and_b64 s[0:1], s[10:11], exec
	s_cselect_b32 s87, 0, 4
	s_lshl_b32 s92, s96, 1
	s_xor_b32 s91, s87, 0x104
	s_lshl_b64 s[0:1], s[92:93], 2
	v_readlane_b32 s4, v243, 24
	s_add_u32 s46, s4, s0
	v_readlane_b32 s0, v243, 25
	s_addc_u32 s47, s0, s1
	s_lshl_b32 s0, s87, 1
	v_writelane_b32 v242, s11, 49
	s_addk_i32 s0, 0xfefc
	v_writelane_b32 v242, s0, 51
	s_mul_i32 s92, s96, 0x3e00
	v_readlane_b32 s4, v242, 32
	s_lshl_b32 s97, s91, 1
	s_cmp_eq_u32 s87, 0
	s_cselect_b32 s98, 8, 0
	s_add_i32 s97, s97, s98
	s_lshl_b64 s[0:1], s[92:93], 2
	v_readlane_b32 s6, v242, 34
	v_readlane_b32 s7, v242, 35
	s_add_u32 s50, s6, s0
	v_readlane_b32 s5, v242, 33
	s_addc_u32 s51, s7, s1
	s_lshl_b32 s52, s96, 9
	s_mov_b32 s53, s93
	v_readlane_b32 s10, v242, 38
	s_lshl_b64 s[4:5], s[52:53], 2
	v_readlane_b32 s11, v242, 39
	s_add_u32 s54, s10, s4
	s_addc_u32 s55, s11, s5
	v_readlane_b32 s12, v242, 26
	v_readlane_b32 s13, v242, 27
	s_add_u32 s58, s12, s4
	v_readlane_b32 s14, v242, 28
	s_addc_u32 s59, s13, s5
	s_lshl_b32 s53, s96, 3
	v_readlane_b32 s15, v242, 29
	s_add_u32 s0, s14, s4
	s_addc_u32 s1, s15, s5
	v_readlane_b32 s6, v242, 24
	v_readlane_b32 s7, v242, 25
	s_add_u32 s72, s6, s4
	s_addc_u32 s73, s7, s5
	v_readlane_b32 s8, v242, 36
	v_readlane_b32 s9, v242, 37
	s_branch .LBB0_364
